# P5 GEMM: LDS tiles staged row-major (8 whole 128B lines per LDS-DMA) with XOR swizzle, on top of the attention LDS-DMA version
# speedup vs baseline: 1.0087x; 1.0036x over previous
; #define PG8_STAGE(bufoff, gbase, voff) do { _Pragma("unroll") for (int _i = 0; _i < 2; ++_i) \
;         __builtin_amdgcn_global_load_lds((const unsigned*)((const char*)(gbase) + (voff)[_i]), (PG8_LAS unsigned*)(lds + (bufoff) + ldsw + _i * 8192), 16, 0, 0); } while (0)
; #define PG8_WAIT_V(n) asm volatile("s_waitcnt vmcnt(" #n ")" ::: "memory")
; #define PG8_BAR __builtin_amdgcn_s_barrier()
; template <class Epi, class Sched, bool ALIGN_EPI = false, bool SP2 = false>
; __device__ __forceinline__ void gemm_phase(PG8_LAS unsigned char* lds, const Gemm g, const Sched& S, const Epi& E) {
;     int tid_ = threadIdx.x; asm volatile("" : "+v"(tid_));
;     const int tid = tid_, wid = __builtin_amdgcn_readfirstlane(tid >> 6), lane = tid & 63, wr = wid >> 2, wc = wid & 3, fr = lane & 15, fq = lane >> 4;
;     const int K = g.K, nt = K / BK;
;     unsigned voffA[2], voffB[2];
; #pragma unroll
;     for (int i = 0; i < 2; ++i) { int R, C; stage_rc(tid * 16 + i * 8192, R, C); const int Rb = Epi::PERM ? ((R & ~31) + perm32(R & 31)) : R;
;         voffA[i] = (unsigned)(R * g.ld + C) * 2u; voffB[i] = (unsigned)(Rb * g.ld + C) * 2u; }
;     const size_t kstep = (size_t)(BK * 2);
;     const size_t hstep = (size_t)HALF * g.ld * 2; const size_t khb = (size_t)K * 2;
;     const size_t tstep = 2 * hstep;
;     const unsigned ldsw = (unsigned)wid * 1024u;
;     const int aoff = lds_byte(wr * 64 + fr, fq * 8), boff = lds_byte(wc * 32 + fr, fq * 8);
;     ...
;     if constexpr (SP2) {
;         PG8_STAGE(PG8_SB(0, 0), cB, voffB); PG8_STAGE(PG8_SB(0, 1), cB + hstep, voffB); PG8_STAGE(PG8_SA(0, 0), cA, voffA); PG8_STAGE(PG8_SA(0, 1), cA + hstep, voffA);
;         if (wr == 1) PG8_BAR;
;         PG8_WAIT_V(2); PG8_BAR;
;         PG8_STAGE(PG8_SB(1, 0), cB + kstep, voffB); PG8_STAGE(PG8_SA(1, 0), cA + kstep, voffA); PG8_STAGE(PG8_SB(1, 1), cB + hstep + kstep, voffB);
.LBB0_959:
	s_cmp_lt_i32 s74, 6
	s_cselect_b64 s[0:1], -1, 0
	s_and_b64 s[0:1], s[0:1], s[2:3]
	s_andn2_b64 vcc, exec, s[0:1]
	s_cbranch_vccnz .LBB0_976
	s_waitcnt vmcnt(0)
	v_mov_b32_e32 v10, v188
	s_cmpk_gt_i32 s33, 0x57f
	v_readfirstlane_b32 s3, v10
	s_cbranch_scc1 .LBB0_976
	v_and_b32_e32 v249, 63, v10
	v_lshrrev_b32_e32 v250, 6, v10
	v_lshrrev_b32_e32 v251, 3, v249
	v_lshl_add_u32 v251, v250, 3, v251
	v_bfe_u32 v252, v251, 1, 3
	v_and_b32_e32 v253, 7, v249
	v_xor_b32_e32 v252, v252, v253
	v_lshlrev_b32_e32 v252, 4, v252
	v_lshl_add_u32 v242, v251, 11, v252
	v_add_u32_e32 v243, 0x20000, v242
	v_and_b32_e32 v253, 0xe3, v251
	v_bfe_u32 v249, v251, 2, 2
	v_lshl_or_b32 v253, v249, 3, v253
	v_bfe_u32 v249, v251, 4, 1
	v_lshl_or_b32 v253, v249, 2, v253
	v_lshl_add_u32 v244, v253, 11, v252
	v_add_u32_e32 v245, 0x20000, v244
	v_and_b32_e32 v249, 15, v10
	v_bfe_u32 v251, v10, 4, 2
	v_lshrrev_b32_e32 v252, 1, v249
	v_xor_b32_e32 v251, v251, v252
	v_lshlrev_b32_e32 v251, 4, v251
	v_lshl_add_u32 v251, v249, 7, v251
	v_lshrrev_b32_e32 v252, 2, v250
	v_lshl_add_u32 v246, v252, 13, v251
	v_and_b32_e32 v252, 3, v250
	v_lshl_add_u32 v247, v252, 12, v251
	v_xor_b32_e32 v248, 64, v247
	v_lshlrev_b32_e32 v0, 4, v10
	s_waitcnt lgkmcnt(0)
	v_add_u32_e32 v1, 0x2000, v0
	v_ashrrev_i32_e32 v2, 31, v1
	v_lshrrev_b32_e32 v2, 22, v2
	v_add_u32_e32 v2, v1, v2
	v_ashrrev_i32_e32 v8, 10, v2
	v_mul_i32_i24_e32 v2, 0x400, v8
	v_sub_u32_e32 v1, v1, v2
	v_lshrrev_b32_e32 v2, 4, v1
	v_bitop3_b32 v1, v2, v1, 32 bitop3:0x6c
	v_ashrrev_i32_e32 v2, 31, v1
	v_lshrrev_b32_e32 v2, 26, v2
	v_add_u32_e32 v2, v1, v2
	v_lshlrev_b32_e32 v3, 3, v8
	v_ashrrev_i32_e32 v9, 6, v2
	v_and_b32_e32 v3, -16, v3
	v_add_u32_e32 v3, v9, v3
	v_and_b32_e32 v4, 3, v9
	s_mov_b32 s2, 0x1fffe0
	v_lshrrev_b32_e32 v5, 2, v3
	v_lshlrev_b32_e32 v6, 1, v3
	v_and_b32_e32 v2, 0xc0, v2
	v_and_or_b32 v4, v3, s2, v4
	v_and_b32_e32 v5, 4, v5
	v_and_b32_e32 v6, 24, v6
	v_sub_u32_e32 v1, v1, v2
	v_mov_b32_e32 v2, 1
	v_or3_b32 v4, v4, v5, v6
	v_lshlrev_b32_e32 v5, 5, v8
	v_ashrrev_i16_sdwa v1, v2, sext(v1) dst_sel:DWORD dst_unused:UNUSED_PAD src0_sel:DWORD src1_sel:BYTE_0
	v_and_b32_e32 v5, 32, v5
	v_bfe_i32 v11, v1, 0, 16
	v_add_lshl_u32 v1, v5, v11, 1
	v_lshl_add_u32 v152, v4, 11, v1
	v_mov_b32_e32 v152, v245
	v_lshl_add_u32 v154, v3, 11, v1
	v_mov_b32_e32 v154, v243
	v_bfe_i32 v1, v10, 27, 1
	v_lshrrev_b32_e32 v1, 22, v1
	v_add_u32_e32 v1, v0, v1
	v_and_b32_e32 v1, 0xfffffc00, v1
	v_sub_u32_e32 v0, v0, v1
	v_lshrrev_b32_e32 v1, 4, v0
	v_ashrrev_i32_e32 v3, 31, v10
	v_bitop3_b32 v0, v1, v0, 32 bitop3:0x6c
	v_lshrrev_b32_e32 v3, 26, v3
	v_ashrrev_i32_e32 v1, 31, v0
	v_add_u32_e32 v3, v10, v3
	s_add_u32 s30, s72, 0xab00000
	v_lshrrev_b32_e32 v1, 26, v1
	v_ashrrev_i32_e32 v13, 6, v3
	s_addc_u32 s31, s73, 0
	v_add_u32_e32 v1, v0, v1
	v_lshlrev_b32_e32 v3, 3, v13
	s_add_u32 s34, s72, 0x1a00000
	v_ashrrev_i32_e32 v12, 6, v1
	v_and_b32_e32 v3, -16, v3
	s_addc_u32 s35, s73, 0
	v_add_u32_e32 v3, v12, v3
	v_and_b32_e32 v4, 3, v12
	s_ashr_i32 s37, s33, 31
	v_and_or_b32 v4, v3, s2, v4
	s_lshr_b32 s2, s37, 29
	s_add_i32 s2, s33, s2
	s_ashr_i32 s10, s3, 6
	s_and_b32 s5, s2, -8
	s_ashr_i32 s4, s3, 8
	s_lshl_b32 s36, s10, 10
	s_sub_i32 s5, s33, s5
	s_cmp_lt_i32 s5, 0
	s_movk_i32 s38, 0xb1
	s_cselect_b32 s6, s38, 0xb0
	s_mul_i32 s5, s5, s6
	s_ashr_i32 s2, s2, 3
	s_add_i32 s5, s5, s2
	s_mul_hi_i32 s2, s5, 0x2e8ba2e9
	s_lshr_b32 s6, s2, 31
	s_ashr_i32 s2, s2, 5
	s_add_i32 s2, s2, s6
	s_lshl_b32 s6, s2, 3
	s_mulk_i32 s2, 0xb0
	s_sub_i32 s5, s5, s2
	s_sext_i32_i16 s2, s5
	s_bfe_u32 s2, s2, 0x3001c
	s_add_i32 s7, s5, s2
	s_sext_i32_i16 s2, s7
	s_and_b32 s7, s7, 0xfff8
	s_sub_i32 s5, s5, s7
	s_sext_i32_i16 s5, s5
	v_lshrrev_b32_e32 v5, 2, v3
	v_lshlrev_b32_e32 v6, 1, v3
	v_and_b32_e32 v1, 0xc0, v1
	s_lshr_b32 s2, s2, 3
	s_add_i32 s22, s6, s5
	v_and_b32_e32 v5, 4, v5
	v_and_b32_e32 v6, 24, v6
	v_sub_u32_e32 v0, v0, v1
	s_ashr_i32 s23, s22, 31
	s_bfe_i64 s[8:9], s[2:3], 0x100000
	v_or3_b32 v4, v4, v5, v6
	v_lshlrev_b32_e32 v5, 5, v13
	v_ashrrev_i16_sdwa v0, v2, sext(v0) dst_sel:DWORD dst_unused:UNUSED_PAD src0_sel:DWORD src1_sel:BYTE_0
	s_lshl_b64 s[6:7], s[22:23], 19
	s_lshl_b64 s[8:9], s[8:9], 19
	v_and_b32_e32 v5, 32, v5
	v_bfe_i32 v14, v0, 0, 16
	s_add_u32 s26, s34, s8
	v_add_lshl_u32 v0, v5, v14, 1
	s_addc_u32 s27, s35, s9
	s_add_i32 s39, s36, 0
	v_lshl_add_u32 v156, v4, 11, v0
	v_mov_b32_e32 v156, v244
	s_add_i32 m0, s39, 0x10000
	v_lshl_add_u32 v158, v3, 11, v0
	v_mov_b32_e32 v158, v242
	global_load_lds_dwordx4 v156, s[26:27]
	s_add_i32 m0, s39, 0x12000
	s_add_u32 s8, s26, 0x40000
	global_load_lds_dwordx4 v152, s[26:27]
	s_addc_u32 s9, s27, 0
	s_add_i32 m0, s39, 0x14000
	v_mov_b32_e32 v161, 0
	global_load_lds_dwordx4 v156, s[8:9]
	s_add_i32 m0, s39, 0x16000
	s_add_u32 s24, s30, s6
	s_addc_u32 s25, s31, s7
	s_add_i32 s40, s39, 0x2000
	global_load_lds_dwordx4 v152, s[8:9]
	s_mov_b32 m0, s39
	s_add_u32 s6, s24, 0x40000
	global_load_lds_dwordx4 v158, s[24:25]
	s_mov_b32 m0, s40
	s_addc_u32 s7, s25, 0
	s_add_i32 s41, s39, 0x4000
	global_load_lds_dwordx4 v154, s[24:25]
	s_mov_b32 m0, s41
	s_add_i32 s42, s39, 0x6000
	global_load_lds_dwordx4 v158, s[6:7]
	s_mov_b32 m0, s42
	v_mov_b32_e32 v157, v161
	global_load_lds_dwordx4 v154, s[6:7]
	v_mov_b32_e32 v153, v161
	v_mov_b32_e32 v159, v161
	v_mov_b32_e32 v155, v161
	s_cmp_eq_u32 s4, 1
	s_mov_b32 s5, 0
	v_lshl_add_u64 v[6:7], s[26:27], 0, v[156:157]
	v_lshl_add_u64 v[4:5], s[26:27], 0, v[152:153]
	v_lshl_add_u64 v[0:1], s[24:25], 0, v[158:159]
	s_cselect_b64 s[6:7], -1, 0
	s_cmp_lg_u32 s4, 1
	v_lshl_add_u64 v[2:3], s[24:25], 0, v[154:155]
	s_cbranch_scc1 .LBB0_963
	s_barrier
; #define PG8_STAGE(bufoff, gbase, voff) do { _Pragma("unroll") for (int _i = 0; _i < 2; ++_i) \
;         __builtin_amdgcn_global_load_lds((const unsigned*)((const char*)(gbase) + (voff)[_i]), (PG8_LAS unsigned*)(lds + (bufoff) + ldsw + _i * 8192), 16, 0, 0); } while (0)
; #define PG8_WAIT_V(n) asm volatile("s_waitcnt vmcnt(" #n ")" ::: "memory")
; #define PG8_BAR __builtin_amdgcn_s_barrier()
; template <class Epi, class Sched, bool ALIGN_EPI = false, bool SP2 = false>
; __device__ __forceinline__ void gemm_phase(PG8_LAS unsigned char* lds, const Gemm g, const Sched& S, const Epi& E) {
;     ...
;     const int aoff = lds_byte(wr * 64 + fr, fq * 8), boff = lds_byte(wc * 32 + fr, fq * 8);
;     ...
;     if constexpr (SP2) {
;         PG8_STAGE(PG8_SB(0, 0), cB, voffB); PG8_STAGE(PG8_SB(0, 1), cB + hstep, voffB); PG8_STAGE(PG8_SA(0, 0), cA, voffA); PG8_STAGE(PG8_SA(0, 1), cA + hstep, voffA);
;         if (wr == 1) PG8_BAR;
;         PG8_WAIT_V(2); PG8_BAR;
;         PG8_STAGE(PG8_SB(1, 0), cB + kstep, voffB); PG8_STAGE(PG8_SA(1, 0), cA + kstep, voffA); PG8_STAGE(PG8_SB(1, 1), cB + hstep + kstep, voffB);
;         PG8_WAIT_V(6); PG8_BAR;
.LBB0_963:
	s_add_u32 s8, s72, 0x4b00000
	s_addc_u32 s9, s73, 0
	s_lshl_b32 s10, s10, 5
	s_and_b32 s15, s10, 0x60
	s_mov_b64 s[10:11], 0x80
	s_add_i32 m0, s39, 0x18000
	v_lshl_add_u64 v[6:7], v[6:7], 0, s[10:11]
	s_lshl_b32 s14, s4, 13
	s_lshl_b32 s16, s15, 7
	s_waitcnt vmcnt(2)
	s_barrier
	global_load_lds_dwordx4 v[6:7], off
	v_lshl_add_u64 v[4:5], v[4:5], 0, s[10:11]
	s_add_i32 m0, s39, 0x1a000
	s_add_i32 s43, s39, 0x8000
	s_add_i32 s44, s39, 0xa000
	global_load_lds_dwordx4 v[4:5], off
	v_lshl_add_u64 v[0:1], v[0:1], 0, s[10:11]
	s_mov_b32 m0, s43
	s_add_u32 s12, s26, 0x40080
	global_load_lds_dwordx4 v[0:1], off
	v_lshl_add_u64 v[0:1], v[2:3], 0, s[10:11]
	s_mov_b32 m0, s44
	s_addc_u32 s13, s27, 0
	global_load_lds_dwordx4 v[0:1], off
	s_add_i32 m0, s39, 0x1c000
	v_lshl_add_u64 v[0:1], s[12:13], 0, v[156:157]
	global_load_lds_dwordx4 v[0:1], off
	v_lshl_add_u64 v[0:1], s[12:13], 0, v[152:153]
	s_add_i32 m0, s39, 0x1e000
	v_bfe_u32 v2, v10, 4, 2
	global_load_lds_dwordx4 v[0:1], off
	v_and_b32_e32 v1, 15, v10
	v_lshlrev_b32_e32 v0, 3, v2
	v_lshlrev_b32_e32 v160, 4, v2
	v_lshlrev_b32_e32 v2, 2, v10
	v_lshl_or_b32 v189, s4, 6, v1
	v_lshl_or_b32 v1, v1, 6, v160
	v_and_b32_e32 v2, 32, v2
	v_bitop3_b32 v4, v1, s14, v2 bitop3:0xde
	v_mov_b32_e32 v4, v246
	v_bitop3_b32 v190, v1, s16, v2 bitop3:0xde
	v_mov_b32_e32 v190, v247
	v_lshlrev_b32_e32 v1, 14, v13
	s_sext_i32_i16 s23, s2
	s_cmpk_lt_u32 s3, 0x100
	v_lshl_add_u64 v[2:3], s[72:73], 0, v[160:161]
	s_mov_b64 s[2:3], 0x100000
	v_and_b32_e32 v1, 0xffff8000, v1
	v_lshl_add_u64 v[162:163], v[2:3], 0, s[2:3]
	v_lshl_add_u32 v1, v12, 11, v1
	v_and_b32_e32 v2, 1, v13
	v_lshl_or_b32 v1, v2, 6, v1
	v_lshl_add_u32 v164, v14, 1, v1
	v_mov_b32_e32 v164, v242
	v_lshlrev_b32_e32 v1, 14, v8
	v_and_b32_e32 v1, 0xffff8000, v1
	v_lshl_add_u32 v1, v9, 11, v1
	v_and_b32_e32 v2, 1, v8
	s_waitcnt vmcnt(6)
	v_lshl_or_b32 v1, v2, 6, v1
	s_cselect_b64 s[12:13], -1, 0
	v_lshl_add_u32 v166, v11, 1, v1
	v_mov_b32_e32 v166, v243
	s_add_i32 s47, 0, 0x10000
	s_add_i32 s48, 0, 0x14000
	v_mbcnt_lo_u32_b32 v1, -1, 0
	s_ashr_i32 s45, s84, 31
	s_mov_b32 s46, s84
	v_mov_b32_e32 v165, v161
	v_mov_b32_e32 v167, v161
	v_mov_b64_e32 v[168:169], 0x580
	v_mov_b64_e32 v[170:171], 0x57f
	v_add_u32_e32 v191, s47, v190
	v_xor_b32_e32 v236, 64, v191
	v_add_u32_e32 v192, s48, v190
	v_xor_b32_e32 v237, 64, v192
	v_add_u32_e32 v193, 0, v4
	v_xor_b32_e32 v238, 64, v193
	v_mbcnt_hi_u32_b32 v194, -1, v1
	v_mov_b32_e32 v195, 0x358637bd
	s_movk_i32 s49, 0x1600
	s_lshl_b32 s4, s15, 1
	v_lshlrev_b32_e32 v160, 1, v0
	s_mov_b32 s50, s5
	s_barrier
	s_branch .LBB0_966

; #define PG8_STAGE(bufoff, gbase, voff) do { _Pragma("unroll") for (int _i = 0; _i < 2; ++_i) \
;         __builtin_amdgcn_global_load_lds((const unsigned*)((const char*)(gbase) + (voff)[_i]), (PG8_LAS unsigned*)(lds + (bufoff) + ldsw + _i * 8192), 16, 0, 0); } while (0)
; #define PG8_LDA(dst, b, h) do { _Pragma("unroll") for (int m = 0; m < 4; ++m) _Pragma("unroll") for (int k = 0; k < 2; ++k) dst[m][k] = *(const PG8_LAS bf16x8*)(lds + PG8_SA(b, h) + aoff + m * 2048 + k * 1024); } while (0)
; #define PG8_LDB(dst, b, h) do { _Pragma("unroll") for (int n = 0; n < 2; ++n) _Pragma("unroll") for (int k = 0; k < 2; ++k) dst[n][k] = *(const PG8_LAS bf16x8*)(lds + PG8_SB(b, h) + boff + n * 2048 + k * 1024); } while (0)
; #define PG8_MMA(ai, bj, At, Bt) do { __builtin_amdgcn_s_setprio(1); _Pragma("unroll") for (int m = 0; m < 4; ++m) _Pragma("unroll") for (int n = 0; n < 2; ++n) _Pragma("unroll") for (int k = 0; k < 2; ++k) \
;         acc[ai][bj][m][n] = __builtin_amdgcn_mfma_f32_16x16x32_bf16(Bt[n][k], At[m][k], acc[ai][bj][m][n], 0, 0, 0); __builtin_amdgcn_s_setprio(0); } while (0)
; #define PG8_WAIT_V(n) asm volatile("s_waitcnt vmcnt(" #n ")" ::: "memory")
; #define PG8_WAIT_L(n) asm volatile("s_waitcnt lgkmcnt(" #n ")" ::: "memory")
; #define PG8_BAR __builtin_amdgcn_s_barrier()
; #define PG8_SCHED __builtin_amdgcn_sched_barrier(0)
; template <class Epi, class Sched, bool ALIGN_EPI = false, bool SP2 = false>
; __device__ __forceinline__ void gemm_phase(PG8_LAS unsigned char* lds, const Gemm g, const Sched& S, const Epi& E) {
;     ...
;             PG8_LDB(B0, 0, 0); PG8_LDB(B1, 0, 1); PG8_SCHED; PG8_LDA(At, 0, 0); PG8_STAGE(PG8_SA(1, 1), a1 + hstep, voffA);
;             PG8_WAIT_V(8); PG8_WAIT_L(0); PG8_BAR; PG8_MMA(0, 0, At, B0); PG8_MMA(0, 1, At, B1); PG8_BAR; PG8_SCHED;
;             PG8_LDA(At, 0, 1); PG8_STAGE(PG8_SB(0, 0), b2, voffB); PG8_STAGE(PG8_SB(0, 1), b2 + hstep, voffB); PG8_STAGE(PG8_SA(0, 0), a2, voffA);
;             PG8_WAIT_V(8); PG8_WAIT_L(0); PG8_BAR; PG8_MMA(1, 0, At, B0); PG8_MMA(1, 1, At, B1); PG8_BAR; PG8_SCHED;
.LBB0_969:
	ds_read_b128 v[128:131], v191
	ds_read_b128 v[132:135], v236
	ds_read_b128 v[136:139], v191 offset:2048
	ds_read_b128 v[140:143], v236 offset:2048
	ds_read_b128 v[144:147], v192
	ds_read_b128 v[148:151], v237
	ds_read_b128 v[172:175], v192 offset:2048
	ds_read_b128 v[176:179], v237 offset:2048
	s_add_u32 s26, s24, 0xfffc0080
	s_addc_u32 s27, s25, -1
	s_cmp_eq_u32 s57, 12
	s_cselect_b32 s29, s17, s27
	s_cselect_b32 s28, s51, s26
	s_cselect_b32 s27, s15, s56
	s_cselect_b32 s26, s54, s55
	v_lshl_add_u64 v[220:221], s[24:25], 0, v[164:165]
	s_add_i32 m0, s39, 0xc000
	ds_read_b128 v[180:183], v193
	ds_read_b128 v[184:187], v238
	ds_read_b128 v[196:199], v193 offset:2048
	ds_read_b128 v[200:203], v238 offset:2048
	ds_read_b128 v[204:207], v193 offset:4096
	ds_read_b128 v[208:211], v238 offset:4096
	ds_read_b128 v[212:215], v193 offset:6144
	ds_read_b128 v[216:219], v238 offset:6144
	global_load_lds_dwordx4 v[220:221], off
	v_lshl_add_u64 v[220:221], s[24:25], 0, v[166:167]
	s_add_i32 m0, s39, 0xe000
	s_nop 0
	global_load_lds_dwordx4 v[220:221], off
	s_waitcnt vmcnt(8)
	s_waitcnt lgkmcnt(0)
	s_barrier
	s_setprio 1
	s_waitcnt lgkmcnt(0)
	v_mfma_f32_16x16x32_bf16 v[124:127], v[128:131], v[180:183], v[124:127]
	v_mfma_f32_16x16x32_bf16 v[120:123], v[136:139], v[180:183], v[120:123]
	v_mfma_f32_16x16x32_bf16 v[108:111], v[128:131], v[196:199], v[108:111]
	v_mfma_f32_16x16x32_bf16 v[104:107], v[136:139], v[196:199], v[104:107]
	v_mfma_f32_16x16x32_bf16 v[92:95], v[128:131], v[204:207], v[92:95]
	v_mfma_f32_16x16x32_bf16 v[84:87], v[136:139], v[204:207], v[84:87]
	v_mfma_f32_16x16x32_bf16 v[76:79], v[128:131], v[212:215], v[76:79]
	v_mfma_f32_16x16x32_bf16 v[72:75], v[136:139], v[212:215], v[72:75]
	v_mfma_f32_16x16x32_bf16 v[124:127], v[132:135], v[184:187], v[124:127]
	v_mfma_f32_16x16x32_bf16 v[120:123], v[140:143], v[184:187], v[120:123]
	v_mfma_f32_16x16x32_bf16 v[108:111], v[132:135], v[200:203], v[108:111]
	v_mfma_f32_16x16x32_bf16 v[104:107], v[140:143], v[200:203], v[104:107]
	v_mfma_f32_16x16x32_bf16 v[92:95], v[132:135], v[208:211], v[92:95]
	v_mfma_f32_16x16x32_bf16 v[84:87], v[140:143], v[208:211], v[84:87]
	v_mfma_f32_16x16x32_bf16 v[76:79], v[132:135], v[216:219], v[76:79]
	v_mfma_f32_16x16x32_bf16 v[72:75], v[140:143], v[216:219], v[72:75]
	s_setprio 0
	s_setprio 1
	v_mfma_f32_16x16x32_bf16 v[116:119], v[144:147], v[180:183], v[116:119]
	v_mfma_f32_16x16x32_bf16 v[112:115], v[172:175], v[180:183], v[112:115]
	v_mfma_f32_16x16x32_bf16 v[100:103], v[144:147], v[196:199], v[100:103]
	v_mfma_f32_16x16x32_bf16 v[96:99], v[172:175], v[196:199], v[96:99]
	v_mfma_f32_16x16x32_bf16 v[88:91], v[144:147], v[204:207], v[88:91]
	v_mfma_f32_16x16x32_bf16 v[80:83], v[172:175], v[204:207], v[80:83]
	v_mfma_f32_16x16x32_bf16 v[68:71], v[144:147], v[212:215], v[68:71]
	v_mfma_f32_16x16x32_bf16 v[64:67], v[172:175], v[212:215], v[64:67]
	v_mfma_f32_16x16x32_bf16 v[116:119], v[148:151], v[184:187], v[116:119]
	v_mfma_f32_16x16x32_bf16 v[112:115], v[176:179], v[184:187], v[112:115]
	v_mfma_f32_16x16x32_bf16 v[100:103], v[148:151], v[200:203], v[100:103]
	v_mfma_f32_16x16x32_bf16 v[96:99], v[176:179], v[200:203], v[96:99]
	v_mfma_f32_16x16x32_bf16 v[88:91], v[148:151], v[208:211], v[88:91]
	v_mfma_f32_16x16x32_bf16 v[80:83], v[176:179], v[208:211], v[80:83]
	v_mfma_f32_16x16x32_bf16 v[68:71], v[148:151], v[216:219], v[68:71]
	v_mfma_f32_16x16x32_bf16 v[64:67], v[176:179], v[216:219], v[64:67]
	s_setprio 0
	s_barrier
	s_add_i32 s58, s47, s36
	v_lshl_add_u64 v[220:221], s[26:27], 0, v[156:157]
	s_mov_b32 m0, s58
	ds_read_b128 v[180:183], v193 offset:16384
	ds_read_b128 v[184:187], v238 offset:16384
	ds_read_b128 v[196:199], v193 offset:18432
	ds_read_b128 v[200:203], v238 offset:18432
	ds_read_b128 v[204:207], v193 offset:20480
	ds_read_b128 v[208:211], v238 offset:20480
	ds_read_b128 v[212:215], v193 offset:22528
	ds_read_b128 v[216:219], v238 offset:22528
	global_load_lds_dwordx4 v[220:221], off
	s_add_i32 m0, s58, 0x2000
	s_add_u32 s58, s26, 0x40000
	v_lshl_add_u64 v[222:223], s[26:27], 0, v[152:153]
	s_addc_u32 s59, s27, 0
	s_add_i32 s60, s48, s36
	global_load_lds_dwordx4 v[222:223], off
	v_lshl_add_u64 v[224:225], s[58:59], 0, v[156:157]
	s_mov_b32 m0, s60
	v_lshl_add_u64 v[226:227], s[28:29], 0, v[154:155]
	global_load_lds_dwordx4 v[224:225], off
	v_lshl_add_u64 v[224:225], s[58:59], 0, v[152:153]
	s_add_i32 m0, s60, 0x2000
	s_nop 0
	global_load_lds_dwordx4 v[224:225], off
	v_lshl_add_u64 v[224:225], s[28:29], 0, v[158:159]
	s_mov_b32 m0, s39
	s_nop 0
	global_load_lds_dwordx4 v[224:225], off
	s_mov_b32 m0, s40
	s_nop 0
	global_load_lds_dwordx4 v[226:227], off
	s_waitcnt vmcnt(8)
	s_waitcnt lgkmcnt(0)
	s_barrier
; #define PG8_STAGE(bufoff, gbase, voff) do { _Pragma("unroll") for (int _i = 0; _i < 2; ++_i) \
;         __builtin_amdgcn_global_load_lds((const unsigned*)((const char*)(gbase) + (voff)[_i]), (PG8_LAS unsigned*)(lds + (bufoff) + ldsw + _i * 8192), 16, 0, 0); } while (0)
; #define PG8_LDA(dst, b, h) do { _Pragma("unroll") for (int m = 0; m < 4; ++m) _Pragma("unroll") for (int k = 0; k < 2; ++k) dst[m][k] = *(const PG8_LAS bf16x8*)(lds + PG8_SA(b, h) + aoff + m * 2048 + k * 1024); } while (0)
; #define PG8_LDB(dst, b, h) do { _Pragma("unroll") for (int n = 0; n < 2; ++n) _Pragma("unroll") for (int k = 0; k < 2; ++k) dst[n][k] = *(const PG8_LAS bf16x8*)(lds + PG8_SB(b, h) + boff + n * 2048 + k * 1024); } while (0)
; #define PG8_MMA(ai, bj, At, Bt) do { __builtin_amdgcn_s_setprio(1); _Pragma("unroll") for (int m = 0; m < 4; ++m) _Pragma("unroll") for (int n = 0; n < 2; ++n) _Pragma("unroll") for (int k = 0; k < 2; ++k) \
;         acc[ai][bj][m][n] = __builtin_amdgcn_mfma_f32_16x16x32_bf16(Bt[n][k], At[m][k], acc[ai][bj][m][n], 0, 0, 0); __builtin_amdgcn_s_setprio(0); } while (0)
; #define PG8_WAIT_V(n) asm volatile("s_waitcnt vmcnt(" #n ")" ::: "memory")
; #define PG8_WAIT_L(n) asm volatile("s_waitcnt lgkmcnt(" #n ")" ::: "memory")
; #define PG8_BAR __builtin_amdgcn_s_barrier()
; #define PG8_SCHED __builtin_amdgcn_sched_barrier(0)
; template <class Epi, class Sched, bool ALIGN_EPI = false, bool SP2 = false>
; __device__ __forceinline__ void gemm_phase(PG8_LAS unsigned char* lds, const Gemm g, const Sched& S, const Epi& E) {
;     ...
;             PG8_WAIT_V(8); PG8_WAIT_L(0); PG8_BAR; PG8_MMA(1, 0, At, B0); PG8_MMA(1, 1, At, B1); PG8_BAR; PG8_SCHED;
;             PG8_LDB(B0, 1, 0); PG8_LDB(B1, 1, 1); PG8_SCHED; PG8_LDA(At, 1, 0); PG8_STAGE(PG8_SA(0, 1), a2 + hstep, voffA);
;             PG8_WAIT_V(8); PG8_WAIT_L(0); PG8_BAR; PG8_MMA(0, 0, At, B0); PG8_MMA(0, 1, At, B1); PG8_BAR; PG8_SCHED;
;             PG8_LDA(At, 1, 1); PG8_STAGE(PG8_SB(1, 0), b3, voffB); PG8_STAGE(PG8_SB(1, 1), b3 + hstep, voffB); PG8_STAGE(PG8_SA(1, 0), a3, voffA);
	s_setprio 1
	s_waitcnt lgkmcnt(0)
	v_mfma_f32_16x16x32_bf16 v[60:63], v[128:131], v[180:183], v[60:63]
	v_mfma_f32_16x16x32_bf16 v[52:55], v[136:139], v[180:183], v[52:55]
	v_mfma_f32_16x16x32_bf16 v[44:47], v[128:131], v[196:199], v[44:47]
	v_mfma_f32_16x16x32_bf16 v[40:43], v[136:139], v[196:199], v[40:43]
	v_mfma_f32_16x16x32_bf16 v[28:31], v[128:131], v[204:207], v[28:31]
	v_mfma_f32_16x16x32_bf16 v[20:23], v[136:139], v[204:207], v[20:23]
	v_mfma_f32_16x16x32_bf16 v[12:15], v[128:131], v[212:215], v[12:15]
	v_mfma_f32_16x16x32_bf16 v[8:11], v[136:139], v[212:215], v[8:11]
	v_mfma_f32_16x16x32_bf16 v[60:63], v[132:135], v[184:187], v[60:63]
	v_mfma_f32_16x16x32_bf16 v[52:55], v[140:143], v[184:187], v[52:55]
	v_mfma_f32_16x16x32_bf16 v[44:47], v[132:135], v[200:203], v[44:47]
	v_mfma_f32_16x16x32_bf16 v[40:43], v[140:143], v[200:203], v[40:43]
	v_mfma_f32_16x16x32_bf16 v[28:31], v[132:135], v[208:211], v[28:31]
	v_mfma_f32_16x16x32_bf16 v[20:23], v[140:143], v[208:211], v[20:23]
	v_mfma_f32_16x16x32_bf16 v[12:15], v[132:135], v[216:219], v[12:15]
	v_mfma_f32_16x16x32_bf16 v[8:11], v[140:143], v[216:219], v[8:11]
	s_setprio 0
	s_setprio 1
	v_mfma_f32_16x16x32_bf16 v[56:59], v[144:147], v[180:183], v[56:59]
	v_mfma_f32_16x16x32_bf16 v[48:51], v[172:175], v[180:183], v[48:51]
	v_mfma_f32_16x16x32_bf16 v[36:39], v[144:147], v[196:199], v[36:39]
	v_mfma_f32_16x16x32_bf16 v[32:35], v[172:175], v[196:199], v[32:35]
	v_mfma_f32_16x16x32_bf16 v[24:27], v[144:147], v[204:207], v[24:27]
	v_mfma_f32_16x16x32_bf16 v[16:19], v[172:175], v[204:207], v[16:19]
	v_mfma_f32_16x16x32_bf16 v[4:7], v[144:147], v[212:215], v[4:7]
	v_mfma_f32_16x16x32_bf16 v[0:3], v[172:175], v[212:215], v[0:3]
	v_mfma_f32_16x16x32_bf16 v[56:59], v[148:151], v[184:187], v[56:59]
	v_mfma_f32_16x16x32_bf16 v[48:51], v[176:179], v[184:187], v[48:51]
	v_mfma_f32_16x16x32_bf16 v[36:39], v[148:151], v[200:203], v[36:39]
	v_mfma_f32_16x16x32_bf16 v[32:35], v[176:179], v[200:203], v[32:35]
	v_mfma_f32_16x16x32_bf16 v[24:27], v[148:151], v[208:211], v[24:27]
	v_mfma_f32_16x16x32_bf16 v[16:19], v[176:179], v[208:211], v[16:19]
	v_mfma_f32_16x16x32_bf16 v[4:7], v[148:151], v[216:219], v[4:7]
	v_mfma_f32_16x16x32_bf16 v[0:3], v[176:179], v[216:219], v[0:3]
	s_setprio 0
	s_barrier
	s_add_i32 s58, 0, 0x18000
	s_add_i32 s59, 0, 0x1c000
	v_add_u32_e32 v140, s58, v190
	v_add_u32_e32 v239, s58, v248
	v_add_u32_e32 v176, s59, v190
	v_add_u32_e32 v240, s59, v248
	ds_read_b128 v[128:131], v140
	ds_read_b128 v[132:135], v239
	ds_read_b128 v[136:139], v140 offset:2048
	ds_read_b128 v[140:143], v239 offset:2048
	ds_read_b128 v[144:147], v176
	ds_read_b128 v[148:151], v240
	ds_read_b128 v[172:175], v176 offset:2048
	ds_read_b128 v[176:179], v240 offset:2048
	s_add_u32 s28, s28, 0x40000
	s_addc_u32 s29, s29, 0
	s_mov_b32 m0, s41
	v_lshl_add_u64 v[228:229], s[28:29], 0, v[158:159]
	ds_read_b128 v[180:183], v193 offset:32768
	ds_read_b128 v[184:187], v238 offset:32768
	ds_read_b128 v[196:199], v193 offset:34816
	ds_read_b128 v[200:203], v238 offset:34816
	ds_read_b128 v[204:207], v193 offset:36864
	ds_read_b128 v[208:211], v238 offset:36864
	ds_read_b128 v[212:215], v193 offset:38912
	ds_read_b128 v[216:219], v238 offset:38912
	global_load_lds_dwordx4 v[228:229], off
	v_lshl_add_u64 v[228:229], s[28:29], 0, v[154:155]
	s_mov_b32 m0, s42
	s_nop 0
	global_load_lds_dwordx4 v[228:229], off
	s_waitcnt vmcnt(8)
	s_waitcnt lgkmcnt(0)
	s_barrier
	s_setprio 1
	s_waitcnt lgkmcnt(0)
	v_mfma_f32_16x16x32_bf16 v[124:127], v[128:131], v[180:183], v[124:127]
	v_mfma_f32_16x16x32_bf16 v[120:123], v[136:139], v[180:183], v[120:123]
	v_mfma_f32_16x16x32_bf16 v[108:111], v[128:131], v[196:199], v[108:111]
	v_mfma_f32_16x16x32_bf16 v[104:107], v[136:139], v[196:199], v[104:107]
	v_mfma_f32_16x16x32_bf16 v[92:95], v[128:131], v[204:207], v[92:95]
	v_mfma_f32_16x16x32_bf16 v[84:87], v[136:139], v[204:207], v[84:87]
	v_mfma_f32_16x16x32_bf16 v[76:79], v[128:131], v[212:215], v[76:79]
	v_mfma_f32_16x16x32_bf16 v[72:75], v[136:139], v[212:215], v[72:75]
	v_mfma_f32_16x16x32_bf16 v[124:127], v[132:135], v[184:187], v[124:127]
	v_mfma_f32_16x16x32_bf16 v[120:123], v[140:143], v[184:187], v[120:123]
	v_mfma_f32_16x16x32_bf16 v[108:111], v[132:135], v[200:203], v[108:111]
	v_mfma_f32_16x16x32_bf16 v[104:107], v[140:143], v[200:203], v[104:107]
	v_mfma_f32_16x16x32_bf16 v[92:95], v[132:135], v[208:211], v[92:95]
	v_mfma_f32_16x16x32_bf16 v[84:87], v[140:143], v[208:211], v[84:87]
	v_mfma_f32_16x16x32_bf16 v[76:79], v[132:135], v[216:219], v[76:79]
	v_mfma_f32_16x16x32_bf16 v[72:75], v[140:143], v[216:219], v[72:75]
	s_setprio 0
	s_setprio 1
	v_mfma_f32_16x16x32_bf16 v[116:119], v[144:147], v[180:183], v[116:119]
	v_mfma_f32_16x16x32_bf16 v[112:115], v[172:175], v[180:183], v[112:115]
	v_mfma_f32_16x16x32_bf16 v[100:103], v[144:147], v[196:199], v[100:103]
	v_mfma_f32_16x16x32_bf16 v[96:99], v[172:175], v[196:199], v[96:99]
	v_mfma_f32_16x16x32_bf16 v[88:91], v[144:147], v[204:207], v[88:91]
	v_mfma_f32_16x16x32_bf16 v[80:83], v[172:175], v[204:207], v[80:83]
	v_mfma_f32_16x16x32_bf16 v[68:71], v[144:147], v[212:215], v[68:71]
	v_mfma_f32_16x16x32_bf16 v[64:67], v[172:175], v[212:215], v[64:67]
	v_mfma_f32_16x16x32_bf16 v[116:119], v[148:151], v[184:187], v[116:119]
	v_mfma_f32_16x16x32_bf16 v[112:115], v[176:179], v[184:187], v[112:115]
	v_mfma_f32_16x16x32_bf16 v[100:103], v[148:151], v[200:203], v[100:103]
	v_mfma_f32_16x16x32_bf16 v[96:99], v[176:179], v[200:203], v[96:99]
	v_mfma_f32_16x16x32_bf16 v[88:91], v[148:151], v[208:211], v[88:91]
	v_mfma_f32_16x16x32_bf16 v[80:83], v[176:179], v[208:211], v[80:83]
	v_mfma_f32_16x16x32_bf16 v[68:71], v[148:151], v[216:219], v[68:71]
	v_mfma_f32_16x16x32_bf16 v[64:67], v[176:179], v[216:219], v[64:67]
	s_setprio 0
	s_barrier
; #define PG8_STAGE(bufoff, gbase, voff) do { _Pragma("unroll") for (int _i = 0; _i < 2; ++_i) \
;         __builtin_amdgcn_global_load_lds((const unsigned*)((const char*)(gbase) + (voff)[_i]), (PG8_LAS unsigned*)(lds + (bufoff) + ldsw + _i * 8192), 16, 0, 0); } while (0)
; #define PG8_LDA(dst, b, h) do { _Pragma("unroll") for (int m = 0; m < 4; ++m) _Pragma("unroll") for (int k = 0; k < 2; ++k) dst[m][k] = *(const PG8_LAS bf16x8*)(lds + PG8_SA(b, h) + aoff + m * 2048 + k * 1024); } while (0)
; #define PG8_MMA(ai, bj, At, Bt) do { __builtin_amdgcn_s_setprio(1); _Pragma("unroll") for (int m = 0; m < 4; ++m) _Pragma("unroll") for (int n = 0; n < 2; ++n) _Pragma("unroll") for (int k = 0; k < 2; ++k) \
;         acc[ai][bj][m][n] = __builtin_amdgcn_mfma_f32_16x16x32_bf16(Bt[n][k], At[m][k], acc[ai][bj][m][n], 0, 0, 0); __builtin_amdgcn_s_setprio(0); } while (0)
; #define PG8_WAIT_V(n) asm volatile("s_waitcnt vmcnt(" #n ")" ::: "memory")
; #define PG8_WAIT_L(n) asm volatile("s_waitcnt lgkmcnt(" #n ")" ::: "memory")
; #define PG8_BAR __builtin_amdgcn_s_barrier()
; #define PG8_SCHED __builtin_amdgcn_sched_barrier(0)
; template <class Epi, class Sched, bool ALIGN_EPI = false, bool SP2 = false>
; __device__ __forceinline__ void gemm_phase(PG8_LAS unsigned char* lds, const Gemm g, const Sched& S, const Epi& E) {
;     ...
;         for (int t = 0; t < nt; t += 2) {
;             const bool last = (t == nt - 2);
;             const char* a1 = cA + (size_t)(t + 1) * kstep;
;             const char* a2 = last ? nA : cA + (size_t)(t + 2) * kstep; const char* b2 = last ? nB : cB + (size_t)(t + 2) * kstep;
;             const char* a3 = a2 + kstep; const char* b3 = b2 + kstep;
;     ...
;             PG8_LDA(At, 1, 1); PG8_STAGE(PG8_SB(1, 0), b3, voffB); PG8_STAGE(PG8_SB(1, 1), b3 + hstep, voffB); PG8_STAGE(PG8_SA(1, 0), a3, voffA);
;             PG8_WAIT_V(8); PG8_WAIT_L(0); PG8_BAR; PG8_MMA(1, 0, At, B0); PG8_MMA(1, 1, At, B1); PG8_BAR; PG8_SCHED;
	s_add_i32 s28, s58, s36
	v_lshl_add_u64 v[220:221], v[220:221], 0, s[10:11]
	s_mov_b32 m0, s28
	ds_read_b128 v[180:183], v193 offset:49152
	ds_read_b128 v[184:187], v238 offset:49152
	ds_read_b128 v[196:199], v193 offset:51200
	ds_read_b128 v[200:203], v238 offset:51200
	ds_read_b128 v[204:207], v193 offset:53248
	ds_read_b128 v[208:211], v238 offset:53248
	ds_read_b128 v[212:215], v193 offset:55296
	ds_read_b128 v[216:219], v238 offset:55296
	global_load_lds_dwordx4 v[220:221], off
	s_add_i32 m0, s28, 0x2000
	s_add_u32 s26, s26, 0x40080
	v_lshl_add_u64 v[220:221], v[222:223], 0, s[10:11]
	s_addc_u32 s27, s27, 0
	s_add_i32 s28, s59, s36
	global_load_lds_dwordx4 v[220:221], off
	v_lshl_add_u64 v[220:221], s[26:27], 0, v[156:157]
	s_mov_b32 m0, s28
	s_nop 0
	global_load_lds_dwordx4 v[220:221], off
	v_lshl_add_u64 v[220:221], s[26:27], 0, v[152:153]
	s_add_i32 m0, s28, 0x2000
	s_nop 0
	global_load_lds_dwordx4 v[220:221], off
	v_lshl_add_u64 v[220:221], v[224:225], 0, s[10:11]
	s_mov_b32 m0, s43
	s_nop 0
	global_load_lds_dwordx4 v[220:221], off
	v_lshl_add_u64 v[220:221], v[226:227], 0, s[10:11]
	s_mov_b32 m0, s44
	s_nop 0
	global_load_lds_dwordx4 v[220:221], off
	s_waitcnt vmcnt(8)
	s_waitcnt lgkmcnt(0)
	s_barrier
	s_setprio 1
	s_waitcnt lgkmcnt(0)
	v_mfma_f32_16x16x32_bf16 v[60:63], v[128:131], v[180:183], v[60:63]
	v_mfma_f32_16x16x32_bf16 v[52:55], v[136:139], v[180:183], v[52:55]
	v_mfma_f32_16x16x32_bf16 v[44:47], v[128:131], v[196:199], v[44:47]
	v_mfma_f32_16x16x32_bf16 v[40:43], v[136:139], v[196:199], v[40:43]
	v_mfma_f32_16x16x32_bf16 v[28:31], v[128:131], v[204:207], v[28:31]
	v_mfma_f32_16x16x32_bf16 v[20:23], v[136:139], v[204:207], v[20:23]
	v_mfma_f32_16x16x32_bf16 v[12:15], v[128:131], v[212:215], v[12:15]
	v_mfma_f32_16x16x32_bf16 v[8:11], v[136:139], v[212:215], v[8:11]
	v_mfma_f32_16x16x32_bf16 v[60:63], v[132:135], v[184:187], v[60:63]
	v_mfma_f32_16x16x32_bf16 v[52:55], v[140:143], v[184:187], v[52:55]
	v_mfma_f32_16x16x32_bf16 v[44:47], v[132:135], v[200:203], v[44:47]
	v_mfma_f32_16x16x32_bf16 v[40:43], v[140:143], v[200:203], v[40:43]
	v_mfma_f32_16x16x32_bf16 v[28:31], v[132:135], v[208:211], v[28:31]
	v_mfma_f32_16x16x32_bf16 v[20:23], v[140:143], v[208:211], v[20:23]
	v_mfma_f32_16x16x32_bf16 v[12:15], v[132:135], v[216:219], v[12:15]
	v_mfma_f32_16x16x32_bf16 v[8:11], v[140:143], v[216:219], v[8:11]
	s_setprio 0
	s_setprio 1
	v_mfma_f32_16x16x32_bf16 v[56:59], v[144:147], v[180:183], v[56:59]
	v_mfma_f32_16x16x32_bf16 v[48:51], v[172:175], v[180:183], v[48:51]
	v_mfma_f32_16x16x32_bf16 v[36:39], v[144:147], v[196:199], v[36:39]
	v_mfma_f32_16x16x32_bf16 v[32:35], v[172:175], v[196:199], v[32:35]
	v_mfma_f32_16x16x32_bf16 v[24:27], v[144:147], v[204:207], v[24:27]
	v_mfma_f32_16x16x32_bf16 v[16:19], v[172:175], v[204:207], v[16:19]
	v_mfma_f32_16x16x32_bf16 v[4:7], v[144:147], v[212:215], v[4:7]
	v_mfma_f32_16x16x32_bf16 v[0:3], v[172:175], v[212:215], v[0:3]
	v_mfma_f32_16x16x32_bf16 v[56:59], v[148:151], v[184:187], v[56:59]
	v_mfma_f32_16x16x32_bf16 v[48:51], v[176:179], v[184:187], v[48:51]
	v_mfma_f32_16x16x32_bf16 v[36:39], v[148:151], v[200:203], v[36:39]
	v_mfma_f32_16x16x32_bf16 v[32:35], v[176:179], v[200:203], v[32:35]
	v_mfma_f32_16x16x32_bf16 v[24:27], v[148:151], v[208:211], v[24:27]
	v_mfma_f32_16x16x32_bf16 v[16:19], v[176:179], v[208:211], v[16:19]
	v_mfma_f32_16x16x32_bf16 v[4:7], v[148:151], v[216:219], v[4:7]
	v_mfma_f32_16x16x32_bf16 v[0:3], v[176:179], v[216:219], v[0:3]
	s_setprio 0
	s_barrier
	s_add_i32 s57, s57, 2
	s_add_u32 s24, s24, 0x100
	s_addc_u32 s25, s25, 0
	s_add_u32 s55, s55, 0x100
	s_addc_u32 s56, s56, 0
	s_cmp_gt_u32 s57, 13
	s_cbranch_scc0 .LBB0_969
	s_and_b64 vcc, exec, s[12:13]
	s_cbranch_vccz .LBB0_972
	s_barrier
